# att13 = att10 + cross-half max merge moved to the rare rescale path + steady-loop back-edge rotation
# baseline (speedup 1.0000x reference)
.LBB0_303:
	ds_read_b64_tr_b16 v[192:193], v215 offset:24576
	ds_read_b64_tr_b16 v[194:195], v215 offset:25088
	s_waitcnt lgkmcnt(9)
	v_mfma_f32_32x32x16_bf16 v[112:127], v[96:99], v[188:191], v[80:95]
	v_add_f32_e32 v100, v144, v145
	v_add_f32_e32 v100, v146, v100
	v_add_f32_e32 v100, v147, v100
	v_add_f32_e32 v100, v148, v100
	v_add_f32_e32 v100, v149, v100
	v_cvt_pk_bf16_f32 v180, v144, v145
	v_cvt_pk_bf16_f32 v181, v146, v147
	ds_read_b64_tr_b16 v[144:145], v215 offset:28672
	ds_read_b64_tr_b16 v[146:147], v215 offset:29184
	v_add_f32_e32 v96, v150, v100
	v_add_f32_e32 v96, v151, v96
	v_add_f32_e32 v96, v152, v96
	v_add_f32_e32 v160, v153, v96
	s_waitcnt lgkmcnt(10)
	v_mfma_f32_32x32x16_bf16 v[96:111], v[204:207], v[188:191], v[80:95]
	v_cvt_pk_bf16_f32 v182, v148, v149
	v_cvt_pk_bf16_f32 v183, v150, v151
	ds_read_b64_tr_b16 v[148:149], v215 offset:25600
	ds_read_b64_tr_b16 v[150:151], v215 offset:26112
	s_waitcnt lgkmcnt(11)
	v_mfma_f32_32x32x16_bf16 v[112:127], v[208:211], v[184:187], v[112:127]
	v_add_f32_e32 v160, v154, v160
	v_add_f32_e32 v160, v155, v160
	v_add_f32_e32 v160, v156, v160
	v_add_f32_e32 v160, v157, v160
	v_cvt_pk_bf16_f32 v172, v152, v153
	v_cvt_pk_bf16_f32 v173, v154, v155
	ds_read_b64_tr_b16 v[152:153], v215 offset:29696
	ds_read_b64_tr_b16 v[154:155], v215 offset:30208
	s_waitcnt lgkmcnt(12)
	v_mfma_f32_32x32x16_bf16 v[96:111], v[200:203], v[184:187], v[96:111]
	v_add_f32_e32 v160, v158, v160
	v_add_f32_e32 v160, v159, v160
	v_add_f32_e32 v160, v128, v160
	v_add_f32_e32 v160, v129, v160
	v_cvt_pk_bf16_f32 v174, v156, v157
	v_cvt_pk_bf16_f32 v175, v158, v159
	ds_read_b64_tr_b16 v[156:157], v215 offset:26624
	ds_read_b64_tr_b16 v[158:159], v215 offset:27136
	s_waitcnt lgkmcnt(13)
	v_mfma_f32_32x32x16_bf16 v[112:127], v[196:199], v[176:179], v[112:127]
	v_add_f32_e32 v160, v130, v160
	v_add_f32_e32 v160, v131, v160
	v_add_f32_e32 v160, v132, v160
	v_add_f32_e32 v160, v133, v160
	v_cvt_pk_bf16_f32 v164, v128, v129
	v_cvt_pk_bf16_f32 v165, v130, v131
	ds_read_b64_tr_b16 v[128:129], v215 offset:30720
	ds_read_b64_tr_b16 v[130:131], v215 offset:31232
	s_waitcnt lgkmcnt(14)
	v_mfma_f32_32x32x16_bf16 v[96:111], v[10:13], v[176:179], v[96:111]
	v_add_f32_e32 v10, v134, v160
	v_add_f32_e32 v10, v135, v10
	v_add_f32_e32 v10, v136, v10
	v_add_f32_e32 v160, v137, v10
	v_cvt_pk_bf16_f32 v166, v132, v133
	v_cvt_pk_bf16_f32 v167, v134, v135
	ds_read_b64_tr_b16 v[10:11], v215 offset:27648
	ds_read_b64_tr_b16 v[12:13], v215 offset:28160
	s_waitcnt lgkmcnt(14)
	v_mfma_f32_32x32x16_bf16 v[112:127], v[6:9], v[168:171], v[112:127]
	v_add_f32_e32 v6, v138, v160
	v_add_f32_e32 v6, v139, v6
	v_add_f32_e32 v6, v140, v6
	v_add_f32_e32 v132, v141, v6
	v_cvt_pk_bf16_f32 v160, v136, v137
	v_cvt_pk_bf16_f32 v161, v138, v139
	ds_read_b64_tr_b16 v[6:7], v215 offset:31744
	ds_read_b64_tr_b16 v[8:9], v215 offset:32256
	v_mfma_f32_32x32x16_bf16 v[96:111], v[2:5], v[168:171], v[96:111]
	v_add_f32_e32 v2, v142, v132
	v_add_f32_e32 v2, v143, v2
	v_add_f32_e32 v250, v214, v2
	v_cvt_pk_bf16_f32 v162, v140, v141
	v_cvt_pk_bf16_f32 v163, v142, v143
	s_add_i32 s0, s19, s46
	s_mov_b32 s1, m0
	s_mov_b32 m0, s0
	s_nop 0
	global_load_lds_dwordx4 v253, s[98:99]
	s_mov_b32 m0, s1
	s_waitcnt lgkmcnt(14)
	v_mfma_f32_32x32x16_bf16 v[16:31], v[180:183], v[192:195], v[16:31]
	v_max_f32_e32 v2, v112, v113
	v_max3_f32 v3, v114, v115, v97
	v_max3_f32 v2, v2, v96, v98
	v_max3_f32 v2, v2, v99, v116
	v_max3_f32 v3, v3, v118, v119
	v_max3_f32 v2, v2, v117, v100
	s_waitcnt lgkmcnt(12)
	v_mfma_f32_32x32x16_bf16 v[32:47], v[180:183], v[144:147], v[32:47]
	v_max3_f32 v3, v3, v102, v103
	v_max3_f32 v2, v2, v101, v120
	v_max3_f32 v3, v3, v122, v123
	v_max3_f32 v2, v2, v121, v104
	v_max3_f32 v3, v3, v106, v107
	v_max3_f32 v2, v2, v105, v124
	s_waitcnt lgkmcnt(10)
	v_mfma_f32_32x32x16_bf16 v[16:31], v[172:175], v[148:151], v[16:31]
	v_max3_f32 v3, v3, v126, v127
	v_max3_f32 v2, v2, v125, v108
	v_max3_f32 v3, v3, v110, v111
	v_max3_f32 v2, v2, v109, v3
	v_cmp_lt_f32_e32 vcc, s25, v2
	s_cmp_lg_u64 vcc, 0
	s_cselect_b64 s[78:79], -1, 0
	s_cbranch_vccnz .LBB0_311
